# LoRA f32-MFMA streams (rw_lora, post1 g-LoRA): operand prefetch distance 4 steps with five register sets (was 2 with three)
# speedup vs baseline: 1.0060x; 1.0060x over previous
.LBB0_944:
	s_lshl_b32 s18, s48, 4
	s_mov_b32 s10, 0xffffde00
	s_mov_b32 s11, -1
	s_mov_b32 s20, 0x2200
	s_mov_b32 s21, 0
	global_load_dword v50, v[2:3], off
	global_load_dword v51, v[4:5], off
	global_load_dword v52, v[6:7], off
	global_load_dword v53, v[8:9], off
	v_or_b32_e32 v20, s18, v220
	v_mad_i64_i32 v[22:23], s[0:1], v20, s23, v[14:15]
	v_lshl_add_u64 v[22:23], v[22:23], 0, s[16:17]
	v_lshl_add_u64 v[26:27], v[22:23], 0, v[0:1]
	v_lshl_add_u64 v[34:35], v[26:27], 0, s[10:11]
	v_lshl_add_u64 v[36:37], v[26:27], 0, s[20:21]
	global_load_ushort v38, v[26:27], off
	global_load_ushort v42, v[34:35], off
	global_load_ushort v46, v[36:37], off
	v_lshl_add_u64 v[28:29], v[22:23], 0, v[18:19]
	v_lshl_add_u64 v[34:35], v[28:29], 0, s[10:11]
	v_lshl_add_u64 v[36:37], v[28:29], 0, s[20:21]
	global_load_ushort v39, v[28:29], off
	global_load_ushort v43, v[34:35], off
	global_load_ushort v47, v[36:37], off
	v_or_b32_e32 v21, s18, v69
	v_mad_i64_i32 v[24:25], s[0:1], v21, s23, v[14:15]
	v_lshl_add_u64 v[24:25], v[24:25], 0, s[16:17]
	v_lshl_add_u64 v[30:31], v[24:25], 0, v[0:1]
	v_lshl_add_u64 v[34:35], v[30:31], 0, s[10:11]
	v_lshl_add_u64 v[36:37], v[30:31], 0, s[20:21]
	global_load_ushort v40, v[30:31], off
	global_load_ushort v44, v[34:35], off
	global_load_ushort v48, v[36:37], off
	v_lshl_add_u64 v[32:33], v[24:25], 0, v[18:19]
	v_lshl_add_u64 v[34:35], v[32:33], 0, s[10:11]
	v_lshl_add_u64 v[36:37], v[32:33], 0, s[20:21]
	global_load_ushort v41, v[32:33], off
	global_load_ushort v45, v[34:35], off
	global_load_ushort v49, v[36:37], off
	s_waitcnt vmcnt(0)
	v_and_b32_e32 v54, v71, v20
	v_lshlrev_b32_e32 v55, 16, v38
	v_lshlrev_b32_e32 v56, 16, v42
	v_lshlrev_b32_e32 v57, 16, v46
	v_cmp_ne_u32_e32 vcc, 0, v54
	s_nop 1
	v_cndmask_b32_e32 v56, 0, v56, vcc
	v_cmp_ne_u32_e32 vcc, s22, v54
	s_nop 1
	v_cndmask_b32_e32 v57, 0, v57, vcc
	v_sub_f32_e32 v56, v56, v55
	v_sub_f32_e32 v57, v57, v55
	v_mul_f32_e32 v56, v56, v50
	v_mul_f32_e32 v57, v57, v51
	v_add_f32_e32 v56, v56, v55
	v_add_f32_e32 v56, v56, v57
	v_add_f32_e64 v57, |v56|, |v56|
	v_mul_f32_e32 v58, 0x3fb8aa3b, v57
	v_rndne_f32_e32 v59, v58
	v_sub_f32_e32 v60, v58, v59
	v_fma_f32 v58, v57, s35, -v58
	v_fmac_f32_e32 v58, 0x32a5705f, v57
	v_add_f32_e32 v58, v60, v58
	v_cvt_i32_f32_e32 v59, v59
	v_exp_f32_e32 v58, v58
	v_cmp_ngt_f32_e32 vcc, s44, v57
	v_ldexp_f32 v58, v58, v59
	s_nop 0
	v_cndmask_b32_e32 v58, 0, v58, vcc
	v_cmp_nlt_f32_e32 vcc, s45, v57
	s_nop 1
	v_cndmask_b32_e32 v57, v73, v58, vcc
	v_add_f32_e32 v57, 1.0, v57
	v_rcp_f32_e32 v57, v57
	s_nop 0
	v_fma_f32 v58, v57, -2.0, 1.0
	v_mul_f32_e32 v57, v56, v56
	v_fmamk_f32 v59, v57, 0xbbbac73d, v72
	v_fmaak_f32 v59, v57, v59, 0xbd5c1c4e
	v_fmaak_f32 v59, v57, v59, 0x3e088382
	v_fmaak_f32 v59, v57, v59, 0xbeaaaa99
	v_mul_f32_e64 v59, |v56|, v59
	v_fma_f32 v59, v57, v59, |v56|
	v_cmp_nlt_f32_e64 vcc, |v56|, s34
	s_nop 1
	v_cndmask_b32_e32 v58, v59, v58, vcc
	v_bfi_b32 v56, s46, v58, v56
	ds_write_b32 v68, v56
	v_and_b32_e32 v54, v71, v20
	v_lshlrev_b32_e32 v55, 16, v39
	v_lshlrev_b32_e32 v56, 16, v43
	v_lshlrev_b32_e32 v57, 16, v47
	v_cmp_ne_u32_e32 vcc, 0, v54
	s_nop 1
	v_cndmask_b32_e32 v56, 0, v56, vcc
	v_cmp_ne_u32_e32 vcc, s22, v54
	s_nop 1
	v_cndmask_b32_e32 v57, 0, v57, vcc
	v_sub_f32_e32 v56, v56, v55
	v_sub_f32_e32 v57, v57, v55
	v_mul_f32_e32 v56, v56, v52
	v_mul_f32_e32 v57, v57, v53
	v_add_f32_e32 v56, v56, v55
	v_add_f32_e32 v56, v56, v57
	ds_write_b32 v68, v56 offset:4096
	v_and_b32_e32 v54, v71, v21
	v_lshlrev_b32_e32 v55, 16, v40
	v_lshlrev_b32_e32 v56, 16, v44
	v_lshlrev_b32_e32 v57, 16, v48
	v_cmp_ne_u32_e32 vcc, 0, v54
	s_nop 1
	v_cndmask_b32_e32 v56, 0, v56, vcc
	v_cmp_ne_u32_e32 vcc, s22, v54
	s_nop 1
	v_cndmask_b32_e32 v57, 0, v57, vcc
	v_sub_f32_e32 v56, v56, v55
	v_sub_f32_e32 v57, v57, v55
	v_mul_f32_e32 v56, v56, v50
	v_mul_f32_e32 v57, v57, v51
	v_add_f32_e32 v56, v56, v55
	v_add_f32_e32 v56, v56, v57
	v_add_f32_e64 v57, |v56|, |v56|
	v_mul_f32_e32 v58, 0x3fb8aa3b, v57
	v_rndne_f32_e32 v59, v58
	v_sub_f32_e32 v60, v58, v59
	v_fma_f32 v58, v57, s35, -v58
	v_fmac_f32_e32 v58, 0x32a5705f, v57
	v_add_f32_e32 v58, v60, v58
	v_cvt_i32_f32_e32 v59, v59
	v_exp_f32_e32 v58, v58
	v_cmp_ngt_f32_e32 vcc, s44, v57
	v_ldexp_f32 v58, v58, v59
	s_nop 0
	v_cndmask_b32_e32 v58, 0, v58, vcc
	v_cmp_nlt_f32_e32 vcc, s45, v57
	s_nop 1
	v_cndmask_b32_e32 v57, v73, v58, vcc
	v_add_f32_e32 v57, 1.0, v57
	v_rcp_f32_e32 v57, v57
	s_nop 0
	v_fma_f32 v58, v57, -2.0, 1.0
	v_mul_f32_e32 v57, v56, v56
	v_fmamk_f32 v59, v57, 0xbbbac73d, v72
	v_fmaak_f32 v59, v57, v59, 0xbd5c1c4e
	v_fmaak_f32 v59, v57, v59, 0x3e088382
	v_fmaak_f32 v59, v57, v59, 0xbeaaaa99
	v_mul_f32_e64 v59, |v56|, v59
	v_fma_f32 v59, v57, v59, |v56|
	v_cmp_nlt_f32_e64 vcc, |v56|, s34
	s_nop 1
	v_cndmask_b32_e32 v58, v59, v58, vcc
	v_bfi_b32 v56, s46, v58, v56
	ds_write_b32 v70, v56
	v_and_b32_e32 v54, v71, v21
	v_lshlrev_b32_e32 v55, 16, v41
	v_lshlrev_b32_e32 v56, 16, v45
	v_lshlrev_b32_e32 v57, 16, v49
	v_cmp_ne_u32_e32 vcc, 0, v54
	s_nop 1
	v_cndmask_b32_e32 v56, 0, v56, vcc
	v_cmp_ne_u32_e32 vcc, s22, v54
	s_nop 1
	v_cndmask_b32_e32 v57, 0, v57, vcc
	v_sub_f32_e32 v56, v56, v55
	v_sub_f32_e32 v57, v57, v55
	v_mul_f32_e32 v56, v56, v52
	v_mul_f32_e32 v57, v57, v53
	v_add_f32_e32 v56, v56, v55
	v_add_f32_e32 v56, v56, v57
	ds_write_b32 v70, v56 offset:4096
	s_waitcnt lgkmcnt(0)
	s_barrier
	v_and_b32_e32 v112, 63, v164
	v_lshrrev_b32_e32 v113, 6, v164
	v_lshlrev_b32_e32 v107, 2, v112
	v_lshrrev_b32_e32 v114, 4, v112
	v_and_b32_e32 v115, 15, v112
	v_lshlrev_b32_e32 v111, 11, v114
	v_lshl_add_u32 v111, v113, 8, v111
	v_lshl_add_u32 v111, v115, 4, v111
	v_mul_u32_u24_e32 v110, 0x3000, v113
	v_add_u32_e32 v110, 0x2000, v110
	v_lshl_add_u32 v109, v114, 10, v110
	v_lshl_add_u32 v109, v115, 4, v109
	v_lshl_add_u32 v110, v112, 2, v110
	v_readlane_b32 s50, v255, 27
	v_readlane_b32 s51, v255, 28
	v_readlane_b32 s54, v255, 31
	v_readlane_b32 s55, v255, 32
	s_add_u32 s52, s50, 0x20000
	s_addc_u32 s53, s51, 0
	v_mov_b32_e32 v108, v111
	global_load_dwordx4 v[92:95], v108, s[50:51]
	v_add_u32_e32 v108, 0x2000, v108
	ds_read_b32 v104, v107 offset:0
	global_load_dwordx4 v[96:99], v108, s[50:51]
	v_add_u32_e32 v108, 0x2000, v108
	ds_read_b32 v105, v107 offset:256
	global_load_dwordx4 v[100:103], v108, s[50:51]
	v_add_u32_e32 v108, 0x2000, v108
	ds_read_b32 v106, v107 offset:512
	global_load_dwordx4 v[20:23], v108, s[50:51]
	v_add_u32_e32 v108, 0x2000, v108
	ds_read_b32 v28, v107 offset:768
	global_load_dwordx4 v[24:27], v108, s[50:51]
	v_add_u32_e32 v108, 0x2000, v108
	ds_read_b32 v29, v107 offset:1024
	s_waitcnt vmcnt(4) lgkmcnt(4)
	v_mfma_f32_16x16x4_f32 v[76:79], v104, v92, 0
	v_mfma_f32_16x16x4_f32 v[80:83], v104, v93, 0
	v_mfma_f32_16x16x4_f32 v[84:87], v104, v94, 0
	v_mfma_f32_16x16x4_f32 v[88:91], v104, v95, 0
	global_load_dwordx4 v[92:95], v108, s[50:51]
	v_add_u32_e32 v108, 0x2000, v108
	ds_read_b32 v104, v107 offset:1280
	s_waitcnt vmcnt(4) lgkmcnt(4)
	v_mfma_f32_16x16x4_f32 v[76:79], v105, v96, v[76:79]
	v_mfma_f32_16x16x4_f32 v[80:83], v105, v97, v[80:83]
	v_mfma_f32_16x16x4_f32 v[84:87], v105, v98, v[84:87]
	v_mfma_f32_16x16x4_f32 v[88:91], v105, v99, v[88:91]
	global_load_dwordx4 v[96:99], v108, s[50:51]
	v_add_u32_e32 v108, 0x2000, v108
	ds_read_b32 v105, v107 offset:1536
	s_waitcnt vmcnt(4) lgkmcnt(4)
	v_mfma_f32_16x16x4_f32 v[76:79], v106, v100, v[76:79]
	v_mfma_f32_16x16x4_f32 v[80:83], v106, v101, v[80:83]
	v_mfma_f32_16x16x4_f32 v[84:87], v106, v102, v[84:87]
	v_mfma_f32_16x16x4_f32 v[88:91], v106, v103, v[88:91]
	global_load_dwordx4 v[100:103], v108, s[50:51]
	v_add_u32_e32 v108, 0x2000, v108
	ds_read_b32 v106, v107 offset:1792
	s_waitcnt vmcnt(4) lgkmcnt(4)
	v_mfma_f32_16x16x4_f32 v[76:79], v28, v20, v[76:79]
	v_mfma_f32_16x16x4_f32 v[80:83], v28, v21, v[80:83]
	v_mfma_f32_16x16x4_f32 v[84:87], v28, v22, v[84:87]
	v_mfma_f32_16x16x4_f32 v[88:91], v28, v23, v[88:91]
	global_load_dwordx4 v[20:23], v108, s[50:51]
	v_add_u32_e32 v108, 0x2000, v108
	ds_read_b32 v28, v107 offset:2048
	s_waitcnt vmcnt(4) lgkmcnt(4)
	v_mfma_f32_16x16x4_f32 v[76:79], v29, v24, v[76:79]
	v_mfma_f32_16x16x4_f32 v[80:83], v29, v25, v[80:83]
	v_mfma_f32_16x16x4_f32 v[84:87], v29, v26, v[84:87]
	v_mfma_f32_16x16x4_f32 v[88:91], v29, v27, v[88:91]
	global_load_dwordx4 v[24:27], v108, s[50:51]
	v_add_u32_e32 v108, 0x2000, v108
	ds_read_b32 v29, v107 offset:2304
	s_waitcnt vmcnt(4) lgkmcnt(4)
	v_mfma_f32_16x16x4_f32 v[76:79], v104, v92, v[76:79]
	v_mfma_f32_16x16x4_f32 v[80:83], v104, v93, v[80:83]
	v_mfma_f32_16x16x4_f32 v[84:87], v104, v94, v[84:87]
	v_mfma_f32_16x16x4_f32 v[88:91], v104, v95, v[88:91]
	global_load_dwordx4 v[92:95], v108, s[50:51]
	v_add_u32_e32 v108, 0x2000, v108
	ds_read_b32 v104, v107 offset:2560
	s_waitcnt vmcnt(4) lgkmcnt(4)
	v_mfma_f32_16x16x4_f32 v[76:79], v105, v96, v[76:79]
	v_mfma_f32_16x16x4_f32 v[80:83], v105, v97, v[80:83]
	v_mfma_f32_16x16x4_f32 v[84:87], v105, v98, v[84:87]
	v_mfma_f32_16x16x4_f32 v[88:91], v105, v99, v[88:91]
	global_load_dwordx4 v[96:99], v108, s[50:51]
	v_add_u32_e32 v108, 0x2000, v108
	ds_read_b32 v105, v107 offset:2816
	s_waitcnt vmcnt(4) lgkmcnt(4)
	v_mfma_f32_16x16x4_f32 v[76:79], v106, v100, v[76:79]
	v_mfma_f32_16x16x4_f32 v[80:83], v106, v101, v[80:83]
	v_mfma_f32_16x16x4_f32 v[84:87], v106, v102, v[84:87]
	v_mfma_f32_16x16x4_f32 v[88:91], v106, v103, v[88:91]
	global_load_dwordx4 v[100:103], v108, s[50:51]
	v_add_u32_e32 v108, 0x2000, v108
	ds_read_b32 v106, v107 offset:3072
	s_waitcnt vmcnt(4) lgkmcnt(4)
	v_mfma_f32_16x16x4_f32 v[76:79], v28, v20, v[76:79]
	v_mfma_f32_16x16x4_f32 v[80:83], v28, v21, v[80:83]
	v_mfma_f32_16x16x4_f32 v[84:87], v28, v22, v[84:87]
	v_mfma_f32_16x16x4_f32 v[88:91], v28, v23, v[88:91]
	global_load_dwordx4 v[20:23], v108, s[50:51]
	v_add_u32_e32 v108, 0x2000, v108
	ds_read_b32 v28, v107 offset:3328
	s_waitcnt vmcnt(4) lgkmcnt(4)
	v_mfma_f32_16x16x4_f32 v[76:79], v29, v24, v[76:79]
	v_mfma_f32_16x16x4_f32 v[80:83], v29, v25, v[80:83]
	v_mfma_f32_16x16x4_f32 v[84:87], v29, v26, v[84:87]
	v_mfma_f32_16x16x4_f32 v[88:91], v29, v27, v[88:91]
	global_load_dwordx4 v[24:27], v108, s[50:51]
	v_add_u32_e32 v108, 0x2000, v108
	ds_read_b32 v29, v107 offset:3584
	s_waitcnt vmcnt(4) lgkmcnt(4)
	v_mfma_f32_16x16x4_f32 v[76:79], v104, v92, v[76:79]
	v_mfma_f32_16x16x4_f32 v[80:83], v104, v93, v[80:83]
	v_mfma_f32_16x16x4_f32 v[84:87], v104, v94, v[84:87]
	v_mfma_f32_16x16x4_f32 v[88:91], v104, v95, v[88:91]
	global_load_dwordx4 v[92:95], v108, s[50:51]
	v_add_u32_e32 v108, 0x2000, v108
	ds_read_b32 v104, v107 offset:3840
	s_waitcnt vmcnt(4) lgkmcnt(4)
	v_mfma_f32_16x16x4_f32 v[76:79], v105, v96, v[76:79]
	v_mfma_f32_16x16x4_f32 v[80:83], v105, v97, v[80:83]
	v_mfma_f32_16x16x4_f32 v[84:87], v105, v98, v[84:87]
	v_mfma_f32_16x16x4_f32 v[88:91], v105, v99, v[88:91]
	v_mov_b32_e32 v108, v111
	global_load_dwordx4 v[96:99], v108, s[52:53]
	v_add_u32_e32 v108, 0x2000, v108
	ds_read_b32 v105, v107 offset:0
	s_waitcnt vmcnt(4) lgkmcnt(4)
	v_mfma_f32_16x16x4_f32 v[76:79], v106, v100, v[76:79]
	v_mfma_f32_16x16x4_f32 v[80:83], v106, v101, v[80:83]
	v_mfma_f32_16x16x4_f32 v[84:87], v106, v102, v[84:87]
	v_mfma_f32_16x16x4_f32 v[88:91], v106, v103, v[88:91]
	global_load_dwordx4 v[100:103], v108, s[52:53]
	v_add_u32_e32 v108, 0x2000, v108
	ds_read_b32 v106, v107 offset:256
	s_waitcnt vmcnt(4) lgkmcnt(4)
	v_mfma_f32_16x16x4_f32 v[76:79], v28, v20, v[76:79]
	v_mfma_f32_16x16x4_f32 v[80:83], v28, v21, v[80:83]
	v_mfma_f32_16x16x4_f32 v[84:87], v28, v22, v[84:87]
	v_mfma_f32_16x16x4_f32 v[88:91], v28, v23, v[88:91]
	global_load_dwordx4 v[20:23], v108, s[52:53]
	v_add_u32_e32 v108, 0x2000, v108
	ds_read_b32 v28, v107 offset:512
	s_waitcnt vmcnt(4) lgkmcnt(4)
	v_mfma_f32_16x16x4_f32 v[76:79], v29, v24, v[76:79]
	v_mfma_f32_16x16x4_f32 v[80:83], v29, v25, v[80:83]
	v_mfma_f32_16x16x4_f32 v[84:87], v29, v26, v[84:87]
	v_mfma_f32_16x16x4_f32 v[88:91], v29, v27, v[88:91]
	global_load_dwordx4 v[24:27], v108, s[52:53]
	v_add_u32_e32 v108, 0x2000, v108
	ds_read_b32 v29, v107 offset:768
	s_waitcnt vmcnt(4) lgkmcnt(4)
	v_mfma_f32_16x16x4_f32 v[76:79], v104, v92, v[76:79]
	v_mfma_f32_16x16x4_f32 v[80:83], v104, v93, v[80:83]
	v_mfma_f32_16x16x4_f32 v[84:87], v104, v94, v[84:87]
	v_mfma_f32_16x16x4_f32 v[88:91], v104, v95, v[88:91]
	s_nop 7
	ds_write_b32 v109, v76 offset:0
	ds_write_b32 v109, v77 offset:256
	ds_write_b32 v109, v78 offset:512
	ds_write_b32 v109, v79 offset:768
	ds_write_b32 v109, v80 offset:4
	ds_write_b32 v109, v81 offset:260
	ds_write_b32 v109, v82 offset:516
	ds_write_b32 v109, v83 offset:772
	ds_write_b32 v109, v84 offset:8
	ds_write_b32 v109, v85 offset:264
	ds_write_b32 v109, v86 offset:520
	ds_write_b32 v109, v87 offset:776
	s_nop 15
	s_nop 3
	ds_write_b32 v109, v88 offset:12
	ds_write_b32 v109, v89 offset:268
	ds_write_b32 v109, v90 offset:524
	ds_write_b32 v109, v91 offset:780
	s_waitcnt lgkmcnt(0)
	global_load_dwordx4 v[92:95], v108, s[52:53]
	v_add_u32_e32 v108, 0x2000, v108
	ds_read_b32 v104, v107 offset:1024
	s_waitcnt vmcnt(4) lgkmcnt(4)
	v_mfma_f32_16x16x4_f32 v[76:79], v105, v96, 0
	v_mfma_f32_16x16x4_f32 v[80:83], v105, v97, 0
	v_mfma_f32_16x16x4_f32 v[84:87], v105, v98, 0
	v_mfma_f32_16x16x4_f32 v[88:91], v105, v99, 0
	global_load_dwordx4 v[96:99], v108, s[52:53]
	v_add_u32_e32 v108, 0x2000, v108
	ds_read_b32 v105, v107 offset:1280
	s_waitcnt vmcnt(4) lgkmcnt(4)
	v_mfma_f32_16x16x4_f32 v[76:79], v106, v100, v[76:79]
	v_mfma_f32_16x16x4_f32 v[80:83], v106, v101, v[80:83]
	v_mfma_f32_16x16x4_f32 v[84:87], v106, v102, v[84:87]
	v_mfma_f32_16x16x4_f32 v[88:91], v106, v103, v[88:91]
	global_load_dwordx4 v[100:103], v108, s[52:53]
	v_add_u32_e32 v108, 0x2000, v108
	ds_read_b32 v106, v107 offset:1536
	s_waitcnt vmcnt(4) lgkmcnt(4)
	v_mfma_f32_16x16x4_f32 v[76:79], v28, v20, v[76:79]
	v_mfma_f32_16x16x4_f32 v[80:83], v28, v21, v[80:83]
	v_mfma_f32_16x16x4_f32 v[84:87], v28, v22, v[84:87]
	v_mfma_f32_16x16x4_f32 v[88:91], v28, v23, v[88:91]
	global_load_dwordx4 v[20:23], v108, s[52:53]
	v_add_u32_e32 v108, 0x2000, v108
	ds_read_b32 v28, v107 offset:1792
	s_waitcnt vmcnt(4) lgkmcnt(4)
	v_mfma_f32_16x16x4_f32 v[76:79], v29, v24, v[76:79]
	v_mfma_f32_16x16x4_f32 v[80:83], v29, v25, v[80:83]
	v_mfma_f32_16x16x4_f32 v[84:87], v29, v26, v[84:87]
	v_mfma_f32_16x16x4_f32 v[88:91], v29, v27, v[88:91]
	global_load_dwordx4 v[24:27], v108, s[52:53]
	v_add_u32_e32 v108, 0x2000, v108
	ds_read_b32 v29, v107 offset:2048
	s_waitcnt vmcnt(4) lgkmcnt(4)
	v_mfma_f32_16x16x4_f32 v[76:79], v104, v92, v[76:79]
	v_mfma_f32_16x16x4_f32 v[80:83], v104, v93, v[80:83]
	v_mfma_f32_16x16x4_f32 v[84:87], v104, v94, v[84:87]
	v_mfma_f32_16x16x4_f32 v[88:91], v104, v95, v[88:91]
	global_load_dwordx4 v[92:95], v108, s[52:53]
	v_add_u32_e32 v108, 0x2000, v108
	ds_read_b32 v104, v107 offset:2304
	s_waitcnt vmcnt(4) lgkmcnt(4)
	v_mfma_f32_16x16x4_f32 v[76:79], v105, v96, v[76:79]
	v_mfma_f32_16x16x4_f32 v[80:83], v105, v97, v[80:83]
	v_mfma_f32_16x16x4_f32 v[84:87], v105, v98, v[84:87]
	v_mfma_f32_16x16x4_f32 v[88:91], v105, v99, v[88:91]
	global_load_dwordx4 v[96:99], v108, s[52:53]
	v_add_u32_e32 v108, 0x2000, v108
	ds_read_b32 v105, v107 offset:2560
	s_waitcnt vmcnt(4) lgkmcnt(4)
	v_mfma_f32_16x16x4_f32 v[76:79], v106, v100, v[76:79]
	v_mfma_f32_16x16x4_f32 v[80:83], v106, v101, v[80:83]
	v_mfma_f32_16x16x4_f32 v[84:87], v106, v102, v[84:87]
	v_mfma_f32_16x16x4_f32 v[88:91], v106, v103, v[88:91]
	global_load_dwordx4 v[100:103], v108, s[52:53]
	v_add_u32_e32 v108, 0x2000, v108
	ds_read_b32 v106, v107 offset:2816
	s_waitcnt vmcnt(4) lgkmcnt(4)
	v_mfma_f32_16x16x4_f32 v[76:79], v28, v20, v[76:79]
	v_mfma_f32_16x16x4_f32 v[80:83], v28, v21, v[80:83]
	v_mfma_f32_16x16x4_f32 v[84:87], v28, v22, v[84:87]
	v_mfma_f32_16x16x4_f32 v[88:91], v28, v23, v[88:91]
	global_load_dwordx4 v[20:23], v108, s[52:53]
	v_add_u32_e32 v108, 0x2000, v108
	ds_read_b32 v28, v107 offset:3072
	s_waitcnt vmcnt(4) lgkmcnt(4)
	v_mfma_f32_16x16x4_f32 v[76:79], v29, v24, v[76:79]
	v_mfma_f32_16x16x4_f32 v[80:83], v29, v25, v[80:83]
	v_mfma_f32_16x16x4_f32 v[84:87], v29, v26, v[84:87]
	v_mfma_f32_16x16x4_f32 v[88:91], v29, v27, v[88:91]
	global_load_dwordx4 v[24:27], v108, s[52:53]
	v_add_u32_e32 v108, 0x2000, v108
	ds_read_b32 v29, v107 offset:3328
	s_waitcnt vmcnt(4) lgkmcnt(4)
	v_mfma_f32_16x16x4_f32 v[76:79], v104, v92, v[76:79]
	v_mfma_f32_16x16x4_f32 v[80:83], v104, v93, v[80:83]
	v_mfma_f32_16x16x4_f32 v[84:87], v104, v94, v[84:87]
	v_mfma_f32_16x16x4_f32 v[88:91], v104, v95, v[88:91]
	global_load_dwordx4 v[92:95], v108, s[52:53]
	v_add_u32_e32 v108, 0x2000, v108
	ds_read_b32 v104, v107 offset:3584
	s_waitcnt vmcnt(4) lgkmcnt(4)
	v_mfma_f32_16x16x4_f32 v[76:79], v105, v96, v[76:79]
	v_mfma_f32_16x16x4_f32 v[80:83], v105, v97, v[80:83]
	v_mfma_f32_16x16x4_f32 v[84:87], v105, v98, v[84:87]
	v_mfma_f32_16x16x4_f32 v[88:91], v105, v99, v[88:91]
	global_load_dwordx4 v[96:99], v108, s[52:53]
	v_add_u32_e32 v108, 0x2000, v108
	ds_read_b32 v105, v107 offset:3840
	s_waitcnt vmcnt(4) lgkmcnt(4)
	v_mfma_f32_16x16x4_f32 v[76:79], v106, v100, v[76:79]
	v_mfma_f32_16x16x4_f32 v[80:83], v106, v101, v[80:83]
	v_mfma_f32_16x16x4_f32 v[84:87], v106, v102, v[84:87]
	v_mfma_f32_16x16x4_f32 v[88:91], v106, v103, v[88:91]
	v_mov_b32_e32 v108, v111
	global_load_dwordx4 v[100:103], v108, s[54:55]
	v_add_u32_e32 v108, 0x2000, v108
	ds_read_b32 v106, v107 offset:4096
	s_waitcnt vmcnt(4) lgkmcnt(4)
	v_mfma_f32_16x16x4_f32 v[76:79], v28, v20, v[76:79]
	v_mfma_f32_16x16x4_f32 v[80:83], v28, v21, v[80:83]
	v_mfma_f32_16x16x4_f32 v[84:87], v28, v22, v[84:87]
	v_mfma_f32_16x16x4_f32 v[88:91], v28, v23, v[88:91]
	global_load_dwordx4 v[20:23], v108, s[54:55]
	v_add_u32_e32 v108, 0x2000, v108
	ds_read_b32 v28, v107 offset:4352
	s_waitcnt vmcnt(4) lgkmcnt(4)
	v_mfma_f32_16x16x4_f32 v[76:79], v29, v24, v[76:79]
	v_mfma_f32_16x16x4_f32 v[80:83], v29, v25, v[80:83]
	v_mfma_f32_16x16x4_f32 v[84:87], v29, v26, v[84:87]
	v_mfma_f32_16x16x4_f32 v[88:91], v29, v27, v[88:91]
	global_load_dwordx4 v[24:27], v108, s[54:55]
	v_add_u32_e32 v108, 0x2000, v108
	ds_read_b32 v29, v107 offset:4608
	s_waitcnt vmcnt(4) lgkmcnt(4)
	v_mfma_f32_16x16x4_f32 v[76:79], v104, v92, v[76:79]
	v_mfma_f32_16x16x4_f32 v[80:83], v104, v93, v[80:83]
	v_mfma_f32_16x16x4_f32 v[84:87], v104, v94, v[84:87]
	v_mfma_f32_16x16x4_f32 v[88:91], v104, v95, v[88:91]
	global_load_dwordx4 v[92:95], v108, s[54:55]
	v_add_u32_e32 v108, 0x2000, v108
	ds_read_b32 v104, v107 offset:4864
	s_waitcnt vmcnt(4) lgkmcnt(4)
	v_mfma_f32_16x16x4_f32 v[76:79], v105, v96, v[76:79]
	v_mfma_f32_16x16x4_f32 v[80:83], v105, v97, v[80:83]
	v_mfma_f32_16x16x4_f32 v[84:87], v105, v98, v[84:87]
	v_mfma_f32_16x16x4_f32 v[88:91], v105, v99, v[88:91]
	s_nop 7
	ds_write_b32 v109, v76 offset:4096
	ds_write_b32 v109, v77 offset:4352
	ds_write_b32 v109, v78 offset:4608
	ds_write_b32 v109, v79 offset:4864
	ds_write_b32 v109, v80 offset:4100
	ds_write_b32 v109, v81 offset:4356
	ds_write_b32 v109, v82 offset:4612
	ds_write_b32 v109, v83 offset:4868
	ds_write_b32 v109, v84 offset:4104
	ds_write_b32 v109, v85 offset:4360
	ds_write_b32 v109, v86 offset:4616
	ds_write_b32 v109, v87 offset:4872
	s_nop 15
	s_nop 3
	ds_write_b32 v109, v88 offset:4108
	ds_write_b32 v109, v89 offset:4364
	ds_write_b32 v109, v90 offset:4620
	ds_write_b32 v109, v91 offset:4876
	s_waitcnt lgkmcnt(0)
	global_load_dwordx4 v[96:99], v108, s[54:55]
	v_add_u32_e32 v108, 0x2000, v108
	ds_read_b32 v105, v107 offset:5120
	s_waitcnt vmcnt(4) lgkmcnt(4)
	v_mfma_f32_16x16x4_f32 v[76:79], v106, v100, 0
	v_mfma_f32_16x16x4_f32 v[80:83], v106, v101, 0
	v_mfma_f32_16x16x4_f32 v[84:87], v106, v102, 0
	v_mfma_f32_16x16x4_f32 v[88:91], v106, v103, 0
	global_load_dwordx4 v[100:103], v108, s[54:55]
	v_add_u32_e32 v108, 0x2000, v108
	ds_read_b32 v106, v107 offset:5376
	s_waitcnt vmcnt(4) lgkmcnt(4)
	v_mfma_f32_16x16x4_f32 v[76:79], v28, v20, v[76:79]
	v_mfma_f32_16x16x4_f32 v[80:83], v28, v21, v[80:83]
	v_mfma_f32_16x16x4_f32 v[84:87], v28, v22, v[84:87]
	v_mfma_f32_16x16x4_f32 v[88:91], v28, v23, v[88:91]
	global_load_dwordx4 v[20:23], v108, s[54:55]
	v_add_u32_e32 v108, 0x2000, v108
	ds_read_b32 v28, v107 offset:5632
	s_waitcnt vmcnt(4) lgkmcnt(4)
	v_mfma_f32_16x16x4_f32 v[76:79], v29, v24, v[76:79]
	v_mfma_f32_16x16x4_f32 v[80:83], v29, v25, v[80:83]
	v_mfma_f32_16x16x4_f32 v[84:87], v29, v26, v[84:87]
	v_mfma_f32_16x16x4_f32 v[88:91], v29, v27, v[88:91]
	global_load_dwordx4 v[24:27], v108, s[54:55]
	v_add_u32_e32 v108, 0x2000, v108
	ds_read_b32 v29, v107 offset:5888
	s_waitcnt vmcnt(4) lgkmcnt(4)
	v_mfma_f32_16x16x4_f32 v[76:79], v104, v92, v[76:79]
	v_mfma_f32_16x16x4_f32 v[80:83], v104, v93, v[80:83]
	v_mfma_f32_16x16x4_f32 v[84:87], v104, v94, v[84:87]
	v_mfma_f32_16x16x4_f32 v[88:91], v104, v95, v[88:91]
	global_load_dwordx4 v[92:95], v108, s[54:55]
	v_add_u32_e32 v108, 0x2000, v108
	ds_read_b32 v104, v107 offset:6144
	s_waitcnt vmcnt(4) lgkmcnt(4)
	v_mfma_f32_16x16x4_f32 v[76:79], v105, v96, v[76:79]
	v_mfma_f32_16x16x4_f32 v[80:83], v105, v97, v[80:83]
	v_mfma_f32_16x16x4_f32 v[84:87], v105, v98, v[84:87]
	v_mfma_f32_16x16x4_f32 v[88:91], v105, v99, v[88:91]
	global_load_dwordx4 v[96:99], v108, s[54:55]
	v_add_u32_e32 v108, 0x2000, v108
	ds_read_b32 v105, v107 offset:6400
	s_waitcnt vmcnt(4) lgkmcnt(4)
	v_mfma_f32_16x16x4_f32 v[76:79], v106, v100, v[76:79]
	v_mfma_f32_16x16x4_f32 v[80:83], v106, v101, v[80:83]
	v_mfma_f32_16x16x4_f32 v[84:87], v106, v102, v[84:87]
	v_mfma_f32_16x16x4_f32 v[88:91], v106, v103, v[88:91]
	global_load_dwordx4 v[100:103], v108, s[54:55]
	v_add_u32_e32 v108, 0x2000, v108
	ds_read_b32 v106, v107 offset:6656
	s_waitcnt vmcnt(4) lgkmcnt(4)
	v_mfma_f32_16x16x4_f32 v[76:79], v28, v20, v[76:79]
	v_mfma_f32_16x16x4_f32 v[80:83], v28, v21, v[80:83]
	v_mfma_f32_16x16x4_f32 v[84:87], v28, v22, v[84:87]
	v_mfma_f32_16x16x4_f32 v[88:91], v28, v23, v[88:91]
	global_load_dwordx4 v[20:23], v108, s[54:55]
	v_add_u32_e32 v108, 0x2000, v108
	ds_read_b32 v28, v107 offset:6912
	s_waitcnt vmcnt(4) lgkmcnt(4)
	v_mfma_f32_16x16x4_f32 v[76:79], v29, v24, v[76:79]
	v_mfma_f32_16x16x4_f32 v[80:83], v29, v25, v[80:83]
	v_mfma_f32_16x16x4_f32 v[84:87], v29, v26, v[84:87]
	v_mfma_f32_16x16x4_f32 v[88:91], v29, v27, v[88:91]
	global_load_dwordx4 v[24:27], v108, s[54:55]
	v_add_u32_e32 v108, 0x2000, v108
	ds_read_b32 v29, v107 offset:7168
	s_waitcnt vmcnt(4) lgkmcnt(4)
	v_mfma_f32_16x16x4_f32 v[76:79], v104, v92, v[76:79]
	v_mfma_f32_16x16x4_f32 v[80:83], v104, v93, v[80:83]
	v_mfma_f32_16x16x4_f32 v[84:87], v104, v94, v[84:87]
	v_mfma_f32_16x16x4_f32 v[88:91], v104, v95, v[88:91]
	global_load_dwordx4 v[92:95], v108, s[54:55]
	v_add_u32_e32 v108, 0x2000, v108
	ds_read_b32 v104, v107 offset:7424
	s_waitcnt vmcnt(4) lgkmcnt(4)
	v_mfma_f32_16x16x4_f32 v[76:79], v105, v96, v[76:79]
	v_mfma_f32_16x16x4_f32 v[80:83], v105, v97, v[80:83]
	v_mfma_f32_16x16x4_f32 v[84:87], v105, v98, v[84:87]
	v_mfma_f32_16x16x4_f32 v[88:91], v105, v99, v[88:91]
	global_load_dwordx4 v[96:99], v108, s[54:55]
	v_add_u32_e32 v108, 0x2000, v108
	ds_read_b32 v105, v107 offset:7680
	s_waitcnt vmcnt(4) lgkmcnt(4)
	v_mfma_f32_16x16x4_f32 v[76:79], v106, v100, v[76:79]
	v_mfma_f32_16x16x4_f32 v[80:83], v106, v101, v[80:83]
	v_mfma_f32_16x16x4_f32 v[84:87], v106, v102, v[84:87]
	v_mfma_f32_16x16x4_f32 v[88:91], v106, v103, v[88:91]
	global_load_dwordx4 v[100:103], v108, s[54:55]
	v_add_u32_e32 v108, 0x2000, v108
	ds_read_b32 v106, v107 offset:7936
	s_waitcnt vmcnt(4) lgkmcnt(4)
	v_mfma_f32_16x16x4_f32 v[76:79], v28, v20, v[76:79]
	v_mfma_f32_16x16x4_f32 v[80:83], v28, v21, v[80:83]
	v_mfma_f32_16x16x4_f32 v[84:87], v28, v22, v[84:87]
	v_mfma_f32_16x16x4_f32 v[88:91], v28, v23, v[88:91]
	s_waitcnt vmcnt(3) lgkmcnt(3)
	v_mfma_f32_16x16x4_f32 v[76:79], v29, v24, v[76:79]
	v_mfma_f32_16x16x4_f32 v[80:83], v29, v25, v[80:83]
	v_mfma_f32_16x16x4_f32 v[84:87], v29, v26, v[84:87]
	v_mfma_f32_16x16x4_f32 v[88:91], v29, v27, v[88:91]
	s_waitcnt vmcnt(2) lgkmcnt(2)
	v_mfma_f32_16x16x4_f32 v[76:79], v104, v92, v[76:79]
	v_mfma_f32_16x16x4_f32 v[80:83], v104, v93, v[80:83]
	v_mfma_f32_16x16x4_f32 v[84:87], v104, v94, v[84:87]
	v_mfma_f32_16x16x4_f32 v[88:91], v104, v95, v[88:91]
	s_waitcnt vmcnt(1) lgkmcnt(1)
	v_mfma_f32_16x16x4_f32 v[76:79], v105, v96, v[76:79]
	v_mfma_f32_16x16x4_f32 v[80:83], v105, v97, v[80:83]
	v_mfma_f32_16x16x4_f32 v[84:87], v105, v98, v[84:87]
	v_mfma_f32_16x16x4_f32 v[88:91], v105, v99, v[88:91]
	s_waitcnt vmcnt(0) lgkmcnt(0)
	v_mfma_f32_16x16x4_f32 v[76:79], v106, v100, v[76:79]
	v_mfma_f32_16x16x4_f32 v[80:83], v106, v101, v[80:83]
	v_mfma_f32_16x16x4_f32 v[84:87], v106, v102, v[84:87]
	v_mfma_f32_16x16x4_f32 v[88:91], v106, v103, v[88:91]
	s_nop 7
	ds_write_b32 v109, v76 offset:8192
	ds_write_b32 v109, v77 offset:8448
	ds_write_b32 v109, v78 offset:8704
	ds_write_b32 v109, v79 offset:8960
	ds_write_b32 v109, v80 offset:8196
	ds_write_b32 v109, v81 offset:8452
	ds_write_b32 v109, v82 offset:8708
	ds_write_b32 v109, v83 offset:8964
	ds_write_b32 v109, v84 offset:8200
	ds_write_b32 v109, v85 offset:8456
	ds_write_b32 v109, v86 offset:8712
	ds_write_b32 v109, v87 offset:8968
	s_nop 15
	s_nop 3
	ds_write_b32 v109, v88 offset:8204
	ds_write_b32 v109, v89 offset:8460
	ds_write_b32 v109, v90 offset:8716
	ds_write_b32 v109, v91 offset:8972
	s_waitcnt lgkmcnt(0)
	ds_read2st64_b32 v[62:63], v110 offset0:0 offset1:1
	ds_read2st64_b32 v[56:57], v110 offset0:2 offset1:3
	ds_read2st64_b32 v[50:51], v110 offset0:4 offset1:5
	ds_read2st64_b32 v[44:45], v110 offset0:6 offset1:7
	ds_read2st64_b32 v[38:39], v110 offset0:8 offset1:9
	ds_read2st64_b32 v[32:33], v110 offset0:10 offset1:11
	ds_read2st64_b32 v[26:27], v110 offset0:12 offset1:13
	ds_read2st64_b32 v[20:21], v110 offset0:14 offset1:15
	ds_read2st64_b32 v[64:65], v110 offset0:16 offset1:17
	ds_read2st64_b32 v[58:59], v110 offset0:18 offset1:19
	ds_read2st64_b32 v[52:53], v110 offset0:20 offset1:21
	ds_read2st64_b32 v[46:47], v110 offset0:22 offset1:23
	s_waitcnt lgkmcnt(0)
	ds_read2st64_b32 v[40:41], v110 offset0:24 offset1:25
	ds_read2st64_b32 v[34:35], v110 offset0:26 offset1:27
	ds_read2st64_b32 v[28:29], v110 offset0:28 offset1:29
	ds_read2st64_b32 v[22:23], v110 offset0:30 offset1:31
	ds_read2st64_b32 v[66:67], v110 offset0:32 offset1:33
	ds_read2st64_b32 v[60:61], v110 offset0:34 offset1:35
	ds_read2st64_b32 v[54:55], v110 offset0:36 offset1:37
	ds_read2st64_b32 v[48:49], v110 offset0:38 offset1:39
	ds_read2st64_b32 v[42:43], v110 offset0:40 offset1:41
	ds_read2st64_b32 v[36:37], v110 offset0:42 offset1:43
	ds_read2st64_b32 v[30:31], v110 offset0:44 offset1:45
	ds_read2st64_b32 v[24:25], v110 offset0:46 offset1:47
	s_waitcnt lgkmcnt(0)
	s_waitcnt lgkmcnt(0)
	s_ashr_i32 s19, s18, 31
	s_lshl_b64 s[0:1], s[18:19], 10
	v_lshlrev_b32_e32 v78, 1, v164
	v_or_b32_e32 v74, s0, v78
	v_mov_b32_e32 v75, s1
	s_or_b32 s0, s18, 1
	v_cvt_pk_bf16_f32 v17, v62, v1
	v_lshl_add_u64 v[76:77], s[12:13], 0, v[74:75]
	s_ashr_i32 s1, s0, 31
	global_store_short v[76:77], v17, off
	v_cvt_pk_bf16_f32 v17, v64, v1
	v_lshl_add_u64 v[76:77], s[14:15], 0, v[74:75]
	v_lshl_add_u64 v[74:75], s[92:93], 0, v[74:75]
	s_lshl_b64 s[0:1], s[0:1], 9
	global_store_short v[76:77], v17, off
	v_cvt_pk_bf16_f32 v17, v66, v1
	global_store_short v[74:75], v17, off
	v_lshl_add_u64 v[74:75], s[0:1], 0, v[164:165]
	v_cvt_pk_bf16_f32 v17, v63, v1
	v_lshlrev_b64 v[62:63], 1, v[74:75]
	s_or_b32 s0, s18, 2
	v_lshl_add_u64 v[74:75], s[12:13], 0, v[62:63]
	s_ashr_i32 s1, s0, 31
	global_store_short v[74:75], v17, off
	v_cvt_pk_bf16_f32 v17, v65, v1
	v_lshl_add_u64 v[64:65], s[14:15], 0, v[62:63]
	v_lshl_add_u64 v[62:63], s[92:93], 0, v[62:63]
	s_lshl_b64 s[0:1], s[0:1], 10
	global_store_short v[64:65], v17, off
	v_cvt_pk_bf16_f32 v17, v67, v1
	global_store_short v[62:63], v17, off
	v_or_b32_e32 v62, s0, v78
	v_mov_b32_e32 v63, s1
	s_or_b32 s0, s18, 3
	v_cvt_pk_bf16_f32 v17, v56, v1
	v_lshl_add_u64 v[64:65], s[12:13], 0, v[62:63]
	s_ashr_i32 s1, s0, 31
	global_store_short v[64:65], v17, off
	v_cvt_pk_bf16_f32 v17, v58, v1
	v_lshl_add_u64 v[64:65], s[14:15], 0, v[62:63]
	v_lshl_add_u64 v[62:63], s[92:93], 0, v[62:63]
	s_lshl_b64 s[0:1], s[0:1], 9
	global_store_short v[64:65], v17, off
	v_cvt_pk_bf16_f32 v17, v60, v1
	global_store_short v[62:63], v17, off
	v_lshl_add_u64 v[62:63], s[0:1], 0, v[164:165]
	v_cvt_pk_bf16_f32 v17, v57, v1
	v_lshlrev_b64 v[56:57], 1, v[62:63]
	s_or_b32 s0, s18, 4
	v_lshl_add_u64 v[62:63], s[12:13], 0, v[56:57]
	s_ashr_i32 s1, s0, 31
	global_store_short v[62:63], v17, off
	v_cvt_pk_bf16_f32 v17, v59, v1
	v_lshl_add_u64 v[58:59], s[14:15], 0, v[56:57]
	v_lshl_add_u64 v[56:57], s[92:93], 0, v[56:57]
	s_lshl_b64 s[0:1], s[0:1], 10
	global_store_short v[58:59], v17, off
	v_cvt_pk_bf16_f32 v17, v61, v1
	global_store_short v[56:57], v17, off
	v_or_b32_e32 v56, s0, v78
	v_mov_b32_e32 v57, s1
	s_or_b32 s0, s18, 5
	v_cvt_pk_bf16_f32 v17, v50, v1
	v_lshl_add_u64 v[58:59], s[12:13], 0, v[56:57]
	s_ashr_i32 s1, s0, 31
	global_store_short v[58:59], v17, off
	v_cvt_pk_bf16_f32 v17, v52, v1
	v_lshl_add_u64 v[58:59], s[14:15], 0, v[56:57]
	v_lshl_add_u64 v[56:57], s[92:93], 0, v[56:57]
	s_lshl_b64 s[0:1], s[0:1], 9
	global_store_short v[58:59], v17, off
	v_cvt_pk_bf16_f32 v17, v54, v1
	global_store_short v[56:57], v17, off
	v_lshl_add_u64 v[56:57], s[0:1], 0, v[164:165]
	v_cvt_pk_bf16_f32 v17, v51, v1
	v_lshlrev_b64 v[50:51], 1, v[56:57]
	s_or_b32 s0, s18, 6
	v_lshl_add_u64 v[56:57], s[12:13], 0, v[50:51]
	s_ashr_i32 s1, s0, 31
	global_store_short v[56:57], v17, off
	v_cvt_pk_bf16_f32 v17, v53, v1
	v_lshl_add_u64 v[52:53], s[14:15], 0, v[50:51]
	v_lshl_add_u64 v[50:51], s[92:93], 0, v[50:51]
	s_lshl_b64 s[0:1], s[0:1], 10
	global_store_short v[52:53], v17, off
	v_cvt_pk_bf16_f32 v17, v55, v1
	global_store_short v[50:51], v17, off
	v_or_b32_e32 v50, s0, v78
	v_mov_b32_e32 v51, s1
	s_or_b32 s0, s18, 7
	v_cvt_pk_bf16_f32 v17, v44, v1
	v_lshl_add_u64 v[52:53], s[12:13], 0, v[50:51]
	s_ashr_i32 s1, s0, 31
	global_store_short v[52:53], v17, off
	v_cvt_pk_bf16_f32 v17, v46, v1
	v_lshl_add_u64 v[52:53], s[14:15], 0, v[50:51]
	v_lshl_add_u64 v[50:51], s[92:93], 0, v[50:51]
	s_lshl_b64 s[0:1], s[0:1], 9
	global_store_short v[52:53], v17, off
	v_cvt_pk_bf16_f32 v17, v48, v1
	global_store_short v[50:51], v17, off
	v_lshl_add_u64 v[50:51], s[0:1], 0, v[164:165]
	v_cvt_pk_bf16_f32 v17, v45, v1
	v_lshlrev_b64 v[44:45], 1, v[50:51]
	s_or_b32 s0, s18, 8
	v_lshl_add_u64 v[50:51], s[12:13], 0, v[44:45]
	s_ashr_i32 s1, s0, 31
	global_store_short v[50:51], v17, off
	v_cvt_pk_bf16_f32 v17, v47, v1
	v_lshl_add_u64 v[46:47], s[14:15], 0, v[44:45]
	v_lshl_add_u64 v[44:45], s[92:93], 0, v[44:45]
	s_lshl_b64 s[0:1], s[0:1], 10
	global_store_short v[46:47], v17, off
	v_cvt_pk_bf16_f32 v17, v49, v1
	global_store_short v[44:45], v17, off
	v_or_b32_e32 v44, s0, v78
	v_mov_b32_e32 v45, s1
	s_or_b32 s0, s18, 9
	v_cvt_pk_bf16_f32 v17, v38, v1
	v_lshl_add_u64 v[46:47], s[12:13], 0, v[44:45]
	s_ashr_i32 s1, s0, 31
	global_store_short v[46:47], v17, off
	v_cvt_pk_bf16_f32 v17, v40, v1
	v_lshl_add_u64 v[46:47], s[14:15], 0, v[44:45]
	v_lshl_add_u64 v[44:45], s[92:93], 0, v[44:45]
	s_lshl_b64 s[0:1], s[0:1], 9
	global_store_short v[46:47], v17, off
	v_cvt_pk_bf16_f32 v17, v42, v1
	global_store_short v[44:45], v17, off
	v_lshl_add_u64 v[44:45], s[0:1], 0, v[164:165]
	v_cvt_pk_bf16_f32 v17, v39, v1
	v_lshlrev_b64 v[38:39], 1, v[44:45]
	s_or_b32 s0, s18, 10
	v_lshl_add_u64 v[44:45], s[12:13], 0, v[38:39]
	s_ashr_i32 s1, s0, 31
	global_store_short v[44:45], v17, off
	v_cvt_pk_bf16_f32 v17, v41, v1
	v_lshl_add_u64 v[40:41], s[14:15], 0, v[38:39]
	v_lshl_add_u64 v[38:39], s[92:93], 0, v[38:39]
	s_lshl_b64 s[0:1], s[0:1], 10
	global_store_short v[40:41], v17, off
	v_cvt_pk_bf16_f32 v17, v43, v1
	global_store_short v[38:39], v17, off
	v_or_b32_e32 v38, s0, v78
	v_mov_b32_e32 v39, s1
	s_or_b32 s0, s18, 11
	v_cvt_pk_bf16_f32 v17, v32, v1
	v_lshl_add_u64 v[40:41], s[12:13], 0, v[38:39]
	s_ashr_i32 s1, s0, 31
	global_store_short v[40:41], v17, off
	v_cvt_pk_bf16_f32 v17, v34, v1
	v_lshl_add_u64 v[40:41], s[14:15], 0, v[38:39]
	v_lshl_add_u64 v[38:39], s[92:93], 0, v[38:39]
	s_lshl_b64 s[0:1], s[0:1], 9
	global_store_short v[40:41], v17, off
	v_cvt_pk_bf16_f32 v17, v36, v1
	global_store_short v[38:39], v17, off
	v_lshl_add_u64 v[38:39], s[0:1], 0, v[164:165]
	v_cvt_pk_bf16_f32 v17, v33, v1
	v_lshlrev_b64 v[32:33], 1, v[38:39]
	s_or_b32 s0, s18, 12
	v_lshl_add_u64 v[38:39], s[12:13], 0, v[32:33]
	s_ashr_i32 s1, s0, 31
	global_store_short v[38:39], v17, off
	v_cvt_pk_bf16_f32 v17, v35, v1
	v_lshl_add_u64 v[34:35], s[14:15], 0, v[32:33]
	v_lshl_add_u64 v[32:33], s[92:93], 0, v[32:33]
	s_lshl_b64 s[0:1], s[0:1], 10
	global_store_short v[34:35], v17, off
	v_cvt_pk_bf16_f32 v17, v37, v1
	global_store_short v[32:33], v17, off
	v_or_b32_e32 v32, s0, v78
	v_mov_b32_e32 v33, s1
	s_or_b32 s0, s18, 13
	v_cvt_pk_bf16_f32 v17, v26, v1
	v_lshl_add_u64 v[34:35], s[12:13], 0, v[32:33]
	s_ashr_i32 s1, s0, 31
	global_store_short v[34:35], v17, off
	v_cvt_pk_bf16_f32 v17, v28, v1
	v_lshl_add_u64 v[34:35], s[14:15], 0, v[32:33]
	v_lshl_add_u64 v[32:33], s[92:93], 0, v[32:33]
	s_lshl_b64 s[0:1], s[0:1], 9
	global_store_short v[34:35], v17, off
	v_cvt_pk_bf16_f32 v17, v30, v1
	global_store_short v[32:33], v17, off
	v_lshl_add_u64 v[32:33], s[0:1], 0, v[164:165]
	v_cvt_pk_bf16_f32 v17, v27, v1
	v_lshlrev_b64 v[26:27], 1, v[32:33]
	s_or_b32 s0, s18, 14
	v_lshl_add_u64 v[32:33], s[12:13], 0, v[26:27]
	s_ashr_i32 s1, s0, 31
	global_store_short v[32:33], v17, off
	v_cvt_pk_bf16_f32 v17, v29, v1
	v_lshl_add_u64 v[28:29], s[14:15], 0, v[26:27]
	v_lshl_add_u64 v[26:27], s[92:93], 0, v[26:27]
	s_lshl_b64 s[0:1], s[0:1], 10
	global_store_short v[28:29], v17, off
	v_cvt_pk_bf16_f32 v17, v31, v1
	global_store_short v[26:27], v17, off
	v_or_b32_e32 v26, s0, v78
	v_mov_b32_e32 v27, s1
	s_or_b32 s0, s18, 15
	v_cvt_pk_bf16_f32 v17, v20, v1
	v_lshl_add_u64 v[28:29], s[12:13], 0, v[26:27]
	s_ashr_i32 s1, s0, 31
	global_store_short v[28:29], v17, off
	v_cvt_pk_bf16_f32 v17, v22, v1
	v_lshl_add_u64 v[28:29], s[14:15], 0, v[26:27]
	v_lshl_add_u64 v[26:27], s[92:93], 0, v[26:27]
	s_lshl_b64 s[0:1], s[0:1], 9
	global_store_short v[28:29], v17, off
	v_cvt_pk_bf16_f32 v17, v24, v1
	global_store_short v[26:27], v17, off
	v_lshl_add_u64 v[26:27], s[0:1], 0, v[164:165]
	v_cvt_pk_bf16_f32 v17, v21, v1
	v_lshlrev_b64 v[20:21], 1, v[26:27]
	v_lshl_add_u64 v[26:27], s[12:13], 0, v[20:21]
	s_add_i32 s48, s48, s30
	global_store_short v[26:27], v17, off
	v_cvt_pk_bf16_f32 v17, v23, v1
	v_lshl_add_u64 v[22:23], s[14:15], 0, v[20:21]
	v_lshl_add_u64 v[20:21], s[92:93], 0, v[20:21]
	s_cmpk_gt_i32 s48, 0x3ff
	global_store_short v[22:23], v17, off
	v_cvt_pk_bf16_f32 v17, v25, v1
	global_store_short v[20:21], v17, off
	s_barrier
	s_cbranch_scc0 .LBB0_944

.LBB0_1180:
	s_lshl_b32 s45, s44, 4
	s_mov_b32 s6, 0xffffde00
	s_mov_b32 s7, -1
	s_mov_b32 s24, 0x2200
	s_mov_b32 s25, 0
	v_lshlrev_b32_e32 v98, 1, v100
	global_load_dword v88, v[102:103], off
	global_load_dword v89, v[104:105], off
	v_or_b32_e32 v132, s45, v101
	v_mov_b64_e32 v[136:137], s[38:39]
	v_mad_i64_i32 v[136:137], s[0:1], v132, s35, v[136:137]
	v_lshl_add_u64 v[136:137], v[136:137], 0, v[98:99]
	v_lshl_add_u64 v[136:137], v[136:137], 0, s[20:21]
	v_lshl_add_u64 v[144:145], v[136:137], 0, s[6:7]
	v_lshl_add_u64 v[146:147], v[136:137], 0, s[24:25]
	global_load_ushort v148, v[136:137], off
	global_load_ushort v152, v[144:145], off
	global_load_ushort v156, v[146:147], off
	v_or_b32_e32 v133, s45, v120
	v_mov_b64_e32 v[138:139], s[38:39]
	v_mad_i64_i32 v[138:139], s[0:1], v133, s35, v[138:139]
	v_lshl_add_u64 v[138:139], v[138:139], 0, v[98:99]
	v_lshl_add_u64 v[138:139], v[138:139], 0, s[20:21]
	v_lshl_add_u64 v[144:145], v[138:139], 0, s[6:7]
	v_lshl_add_u64 v[146:147], v[138:139], 0, s[24:25]
	global_load_ushort v149, v[138:139], off
	global_load_ushort v153, v[144:145], off
	global_load_ushort v157, v[146:147], off
	v_or_b32_e32 v134, s45, v122
	v_mov_b64_e32 v[140:141], s[38:39]
	v_mad_i64_i32 v[140:141], s[0:1], v134, s35, v[140:141]
	v_lshl_add_u64 v[140:141], v[140:141], 0, v[98:99]
	v_lshl_add_u64 v[140:141], v[140:141], 0, s[20:21]
	v_lshl_add_u64 v[144:145], v[140:141], 0, s[6:7]
	v_lshl_add_u64 v[146:147], v[140:141], 0, s[24:25]
	global_load_ushort v150, v[140:141], off
	global_load_ushort v154, v[144:145], off
	global_load_ushort v158, v[146:147], off
	v_or_b32_e32 v135, s45, v123
	v_mov_b64_e32 v[142:143], s[38:39]
	v_mad_i64_i32 v[142:143], s[0:1], v135, s35, v[142:143]
	v_lshl_add_u64 v[142:143], v[142:143], 0, v[98:99]
	v_lshl_add_u64 v[142:143], v[142:143], 0, s[20:21]
	v_lshl_add_u64 v[144:145], v[142:143], 0, s[6:7]
	v_lshl_add_u64 v[146:147], v[142:143], 0, s[24:25]
	global_load_ushort v151, v[142:143], off
	global_load_ushort v155, v[144:145], off
	global_load_ushort v159, v[146:147], off
	s_waitcnt vmcnt(0)
	v_and_b32_e32 v90, v127, v132
	v_lshlrev_b32_e32 v91, 16, v148
	v_lshlrev_b32_e32 v92, 16, v152
	v_lshlrev_b32_e32 v93, 16, v156
	v_cmp_ne_u32_e32 vcc, 0, v90
	s_nop 1
	v_cndmask_b32_e32 v92, 0, v92, vcc
	v_cmp_ne_u32_e32 vcc, s40, v90
	s_nop 1
	v_cndmask_b32_e32 v93, 0, v93, vcc
	v_sub_f32_e32 v92, v92, v91
	v_sub_f32_e32 v93, v93, v91
	v_mul_f32_e32 v92, v92, v88
	v_mul_f32_e32 v93, v93, v89
	v_add_f32_e32 v92, v92, v91
	v_add_f32_e32 v92, v92, v93
	v_mul_f32_e32 v92, 0xbfb8aa3b, v92
	v_exp_f32_e32 v92, v92
	s_nop 0
	v_add_f32_e32 v95, 1.0, v92
	v_div_scale_f32 v93, s[0:1], v95, v95, 1.0
	v_rcp_f32_e32 v94, v93
	v_div_scale_f32 v112, vcc, 1.0, v95, 1.0
	v_fma_f32 v113, -v93, v94, 1.0
	v_fmac_f32_e32 v94, v113, v94
	v_mul_f32_e32 v113, v112, v94
	v_fma_f32 v114, -v93, v113, v112
	v_fmac_f32_e32 v113, v114, v94
	v_fma_f32 v93, -v93, v113, v112
	v_div_fmas_f32 v112, v93, v94, v113
	v_div_fixup_f32 v92, v112, v95, 1.0
	ds_write_b32 v109, v92
	v_and_b32_e32 v90, v127, v133
	v_lshlrev_b32_e32 v91, 16, v149
	v_lshlrev_b32_e32 v92, 16, v153
	v_lshlrev_b32_e32 v93, 16, v157
	v_cmp_ne_u32_e32 vcc, 0, v90
	s_nop 1
	v_cndmask_b32_e32 v92, 0, v92, vcc
	v_cmp_ne_u32_e32 vcc, s40, v90
	s_nop 1
	v_cndmask_b32_e32 v93, 0, v93, vcc
	v_sub_f32_e32 v92, v92, v91
	v_sub_f32_e32 v93, v93, v91
	v_mul_f32_e32 v92, v92, v88
	v_mul_f32_e32 v93, v93, v89
	v_add_f32_e32 v92, v92, v91
	v_add_f32_e32 v92, v92, v93
	v_mul_f32_e32 v92, 0xbfb8aa3b, v92
	v_exp_f32_e32 v92, v92
	s_nop 0
	v_add_f32_e32 v95, 1.0, v92
	v_div_scale_f32 v93, s[0:1], v95, v95, 1.0
	v_rcp_f32_e32 v94, v93
	v_div_scale_f32 v112, vcc, 1.0, v95, 1.0
	v_fma_f32 v113, -v93, v94, 1.0
	v_fmac_f32_e32 v94, v113, v94
	v_mul_f32_e32 v113, v112, v94
	v_fma_f32 v114, -v93, v113, v112
	v_fmac_f32_e32 v113, v114, v94
	v_fma_f32 v93, -v93, v113, v112
	v_div_fmas_f32 v112, v93, v94, v113
	v_div_fixup_f32 v92, v112, v95, 1.0
	ds_write_b32 v121, v92
	v_and_b32_e32 v90, v127, v134
	v_lshlrev_b32_e32 v91, 16, v150
	v_lshlrev_b32_e32 v92, 16, v154
	v_lshlrev_b32_e32 v93, 16, v158
	v_cmp_ne_u32_e32 vcc, 0, v90
	s_nop 1
	v_cndmask_b32_e32 v92, 0, v92, vcc
	v_cmp_ne_u32_e32 vcc, s40, v90
	s_nop 1
	v_cndmask_b32_e32 v93, 0, v93, vcc
	v_sub_f32_e32 v92, v92, v91
	v_sub_f32_e32 v93, v93, v91
	v_mul_f32_e32 v92, v92, v88
	v_mul_f32_e32 v93, v93, v89
	v_add_f32_e32 v92, v92, v91
	v_add_f32_e32 v92, v92, v93
	v_mul_f32_e32 v92, 0xbfb8aa3b, v92
	v_exp_f32_e32 v92, v92
	s_nop 0
	v_add_f32_e32 v95, 1.0, v92
	v_div_scale_f32 v93, s[0:1], v95, v95, 1.0
	v_rcp_f32_e32 v94, v93
	v_div_scale_f32 v112, vcc, 1.0, v95, 1.0
	v_fma_f32 v113, -v93, v94, 1.0
	v_fmac_f32_e32 v94, v113, v94
	v_mul_f32_e32 v113, v112, v94
	v_fma_f32 v114, -v93, v113, v112
	v_fmac_f32_e32 v113, v114, v94
	v_fma_f32 v93, -v93, v113, v112
	v_div_fmas_f32 v112, v93, v94, v113
	v_div_fixup_f32 v92, v112, v95, 1.0
	ds_write_b32 v109, v92 offset:32
	v_and_b32_e32 v90, v127, v135
	v_lshlrev_b32_e32 v91, 16, v151
	v_lshlrev_b32_e32 v92, 16, v155
	v_lshlrev_b32_e32 v93, 16, v159
	v_cmp_ne_u32_e32 vcc, 0, v90
	s_nop 1
	v_cndmask_b32_e32 v92, 0, v92, vcc
	v_cmp_ne_u32_e32 vcc, s40, v90
	s_nop 1
	v_cndmask_b32_e32 v93, 0, v93, vcc
	v_sub_f32_e32 v92, v92, v91
	v_sub_f32_e32 v93, v93, v91
	v_mul_f32_e32 v92, v92, v88
	v_mul_f32_e32 v93, v93, v89
	v_add_f32_e32 v92, v92, v91
	v_add_f32_e32 v92, v92, v93
	v_mul_f32_e32 v92, 0xbfb8aa3b, v92
	v_exp_f32_e32 v92, v92
	s_nop 0
	v_add_f32_e32 v95, 1.0, v92
	v_div_scale_f32 v93, s[0:1], v95, v95, 1.0
	v_rcp_f32_e32 v94, v93
	v_div_scale_f32 v112, vcc, 1.0, v95, 1.0
	v_fma_f32 v113, -v93, v94, 1.0
	v_fmac_f32_e32 v94, v113, v94
	v_mul_f32_e32 v113, v112, v94
	v_fma_f32 v114, -v93, v113, v112
	v_fmac_f32_e32 v113, v114, v94
	v_fma_f32 v93, -v93, v113, v112
	v_div_fmas_f32 v112, v93, v94, v113
	v_div_fixup_f32 v92, v112, v95, 1.0
	ds_write_b32 v124, v92
	v_mov_b32_e32 v88, 0
	v_mov_b32_e32 v89, 0
	v_mov_b32_e32 v90, 0
	v_mov_b32_e32 v91, 0
	v_mov_b32_e32 v92, 0
	v_mov_b32_e32 v93, 0
	v_mov_b32_e32 v94, 0
	v_mov_b32_e32 v95, 0
	v_mov_b32_e32 v112, 0
	v_mov_b32_e32 v113, 0
	v_mov_b32_e32 v114, 0
	v_mov_b32_e32 v115, 0
	v_mov_b32_e32 v116, 0
	v_mov_b32_e32 v117, 0
	v_mov_b32_e32 v118, 0
	v_mov_b32_e32 v119, 0
	s_mov_b32 s6, 0
	s_mov_b64 s[0:1], 0
	s_waitcnt lgkmcnt(0)
	s_barrier
	v_readlane_b32 s10, v255, 33
	v_readlane_b32 s11, v255, 34
	v_and_b32_e32 v151, 63, v164
	v_lshrrev_b32_e32 v152, 6, v164
	v_lshlrev_b32_e32 v148, 2, v151
	v_lshrrev_b32_e32 v153, 4, v151
	v_and_b32_e32 v154, 15, v151
	v_lshlrev_b32_e32 v149, 11, v153
	v_lshl_add_u32 v149, v152, 8, v149
	v_lshl_add_u32 v149, v154, 4, v149
	v_lshlrev_b32_e32 v150, 13, v153
	v_lshl_add_u32 v150, v152, 8, v150
	v_lshl_add_u32 v150, v154, 4, v150
	v_add_u32_e32 v150, 0x2000, v150
	global_load_dwordx4 v[136:139], v149, s[10:11]
	v_add_u32_e32 v149, 0x2000, v149
	ds_read_b32 v132, v148 offset:0
	global_load_dwordx4 v[140:143], v149, s[10:11]
	v_add_u32_e32 v149, 0x2000, v149
	ds_read_b32 v133, v148 offset:256
	global_load_dwordx4 v[144:147], v149, s[10:11]
	v_add_u32_e32 v149, 0x2000, v149
	ds_read_b32 v134, v148 offset:512
	global_load_dwordx4 v[156:159], v149, s[10:11]
	v_add_u32_e32 v149, 0x2000, v149
	ds_read_b32 v155, v148 offset:768
	global_load_dwordx4 v[160:163], v149, s[10:11]
	v_add_u32_e32 v149, 0x2000, v149
	ds_read_b32 v135, v148 offset:1024
	s_waitcnt vmcnt(4) lgkmcnt(4)
	v_mfma_f32_16x16x4_f32 v[88:91], v132, v136, v[88:91]
	v_mfma_f32_16x16x4_f32 v[92:95], v132, v137, v[92:95]
	v_mfma_f32_16x16x4_f32 v[112:115], v132, v138, v[112:115]
	v_mfma_f32_16x16x4_f32 v[116:119], v132, v139, v[116:119]
	global_load_dwordx4 v[136:139], v149, s[10:11]
	v_add_u32_e32 v149, 0x2000, v149
	ds_read_b32 v132, v148 offset:1280
	s_waitcnt vmcnt(4) lgkmcnt(4)
	v_mfma_f32_16x16x4_f32 v[88:91], v133, v140, v[88:91]
	v_mfma_f32_16x16x4_f32 v[92:95], v133, v141, v[92:95]
	v_mfma_f32_16x16x4_f32 v[112:115], v133, v142, v[112:115]
	v_mfma_f32_16x16x4_f32 v[116:119], v133, v143, v[116:119]
	global_load_dwordx4 v[140:143], v149, s[10:11]
	v_add_u32_e32 v149, 0x2000, v149
	ds_read_b32 v133, v148 offset:1536
	s_waitcnt vmcnt(4) lgkmcnt(4)
	v_mfma_f32_16x16x4_f32 v[88:91], v134, v144, v[88:91]
	v_mfma_f32_16x16x4_f32 v[92:95], v134, v145, v[92:95]
	v_mfma_f32_16x16x4_f32 v[112:115], v134, v146, v[112:115]
	v_mfma_f32_16x16x4_f32 v[116:119], v134, v147, v[116:119]
	global_load_dwordx4 v[144:147], v149, s[10:11]
	v_add_u32_e32 v149, 0x2000, v149
	ds_read_b32 v134, v148 offset:1792
	s_waitcnt vmcnt(4) lgkmcnt(4)
	v_mfma_f32_16x16x4_f32 v[88:91], v155, v156, v[88:91]
	v_mfma_f32_16x16x4_f32 v[92:95], v155, v157, v[92:95]
	v_mfma_f32_16x16x4_f32 v[112:115], v155, v158, v[112:115]
	v_mfma_f32_16x16x4_f32 v[116:119], v155, v159, v[116:119]
	global_load_dwordx4 v[156:159], v149, s[10:11]
	v_add_u32_e32 v149, 0x2000, v149
	ds_read_b32 v155, v148 offset:2048
	s_waitcnt vmcnt(4) lgkmcnt(4)
	v_mfma_f32_16x16x4_f32 v[88:91], v135, v160, v[88:91]
	v_mfma_f32_16x16x4_f32 v[92:95], v135, v161, v[92:95]
	v_mfma_f32_16x16x4_f32 v[112:115], v135, v162, v[112:115]
	v_mfma_f32_16x16x4_f32 v[116:119], v135, v163, v[116:119]
	global_load_dwordx4 v[160:163], v149, s[10:11]
	v_add_u32_e32 v149, 0x2000, v149
	ds_read_b32 v135, v148 offset:2304
	s_waitcnt vmcnt(4) lgkmcnt(4)
	v_mfma_f32_16x16x4_f32 v[88:91], v132, v136, v[88:91]
	v_mfma_f32_16x16x4_f32 v[92:95], v132, v137, v[92:95]
	v_mfma_f32_16x16x4_f32 v[112:115], v132, v138, v[112:115]
	v_mfma_f32_16x16x4_f32 v[116:119], v132, v139, v[116:119]
	global_load_dwordx4 v[136:139], v149, s[10:11]
	v_add_u32_e32 v149, 0x2000, v149
	ds_read_b32 v132, v148 offset:2560
	s_waitcnt vmcnt(4) lgkmcnt(4)
	v_mfma_f32_16x16x4_f32 v[88:91], v133, v140, v[88:91]
	v_mfma_f32_16x16x4_f32 v[92:95], v133, v141, v[92:95]
	v_mfma_f32_16x16x4_f32 v[112:115], v133, v142, v[112:115]
	v_mfma_f32_16x16x4_f32 v[116:119], v133, v143, v[116:119]
	global_load_dwordx4 v[140:143], v149, s[10:11]
	v_add_u32_e32 v149, 0x2000, v149
	ds_read_b32 v133, v148 offset:2816
	s_waitcnt vmcnt(4) lgkmcnt(4)
	v_mfma_f32_16x16x4_f32 v[88:91], v134, v144, v[88:91]
	v_mfma_f32_16x16x4_f32 v[92:95], v134, v145, v[92:95]
	v_mfma_f32_16x16x4_f32 v[112:115], v134, v146, v[112:115]
	v_mfma_f32_16x16x4_f32 v[116:119], v134, v147, v[116:119]
	global_load_dwordx4 v[144:147], v149, s[10:11]
	v_add_u32_e32 v149, 0x2000, v149
	ds_read_b32 v134, v148 offset:3072
	s_waitcnt vmcnt(4) lgkmcnt(4)
	v_mfma_f32_16x16x4_f32 v[88:91], v155, v156, v[88:91]
	v_mfma_f32_16x16x4_f32 v[92:95], v155, v157, v[92:95]
	v_mfma_f32_16x16x4_f32 v[112:115], v155, v158, v[112:115]
	v_mfma_f32_16x16x4_f32 v[116:119], v155, v159, v[116:119]
	global_load_dwordx4 v[156:159], v149, s[10:11]
	v_add_u32_e32 v149, 0x2000, v149
	ds_read_b32 v155, v148 offset:3328
	s_waitcnt vmcnt(4) lgkmcnt(4)
	v_mfma_f32_16x16x4_f32 v[88:91], v135, v160, v[88:91]
	v_mfma_f32_16x16x4_f32 v[92:95], v135, v161, v[92:95]
	v_mfma_f32_16x16x4_f32 v[112:115], v135, v162, v[112:115]
	v_mfma_f32_16x16x4_f32 v[116:119], v135, v163, v[116:119]
	global_load_dwordx4 v[160:163], v149, s[10:11]
	v_add_u32_e32 v149, 0x2000, v149
	ds_read_b32 v135, v148 offset:3584
	s_waitcnt vmcnt(4) lgkmcnt(4)
	v_mfma_f32_16x16x4_f32 v[88:91], v132, v136, v[88:91]
	v_mfma_f32_16x16x4_f32 v[92:95], v132, v137, v[92:95]
	v_mfma_f32_16x16x4_f32 v[112:115], v132, v138, v[112:115]
	v_mfma_f32_16x16x4_f32 v[116:119], v132, v139, v[116:119]
	global_load_dwordx4 v[136:139], v149, s[10:11]
	v_add_u32_e32 v149, 0x2000, v149
	ds_read_b32 v132, v148 offset:3840
	s_waitcnt vmcnt(4) lgkmcnt(4)
	v_mfma_f32_16x16x4_f32 v[88:91], v133, v140, v[88:91]
	v_mfma_f32_16x16x4_f32 v[92:95], v133, v141, v[92:95]
	v_mfma_f32_16x16x4_f32 v[112:115], v133, v142, v[112:115]
	v_mfma_f32_16x16x4_f32 v[116:119], v133, v143, v[116:119]
	global_load_dwordx4 v[140:143], v149, s[10:11]
	v_add_u32_e32 v149, 0x2000, v149
	ds_read_b32 v133, v148 offset:4096
	s_waitcnt vmcnt(4) lgkmcnt(4)
	v_mfma_f32_16x16x4_f32 v[88:91], v134, v144, v[88:91]
	v_mfma_f32_16x16x4_f32 v[92:95], v134, v145, v[92:95]
	v_mfma_f32_16x16x4_f32 v[112:115], v134, v146, v[112:115]
	v_mfma_f32_16x16x4_f32 v[116:119], v134, v147, v[116:119]
	global_load_dwordx4 v[144:147], v149, s[10:11]
	v_add_u32_e32 v149, 0x2000, v149
	ds_read_b32 v134, v148 offset:4352
	s_waitcnt vmcnt(4) lgkmcnt(4)
	v_mfma_f32_16x16x4_f32 v[88:91], v155, v156, v[88:91]
	v_mfma_f32_16x16x4_f32 v[92:95], v155, v157, v[92:95]
	v_mfma_f32_16x16x4_f32 v[112:115], v155, v158, v[112:115]
	v_mfma_f32_16x16x4_f32 v[116:119], v155, v159, v[116:119]
	global_load_dwordx4 v[156:159], v149, s[10:11]
	v_add_u32_e32 v149, 0x2000, v149
	ds_read_b32 v155, v148 offset:4608
	s_waitcnt vmcnt(4) lgkmcnt(4)
	v_mfma_f32_16x16x4_f32 v[88:91], v135, v160, v[88:91]
	v_mfma_f32_16x16x4_f32 v[92:95], v135, v161, v[92:95]
	v_mfma_f32_16x16x4_f32 v[112:115], v135, v162, v[112:115]
	v_mfma_f32_16x16x4_f32 v[116:119], v135, v163, v[116:119]
	global_load_dwordx4 v[160:163], v149, s[10:11]
	v_add_u32_e32 v149, 0x2000, v149
	ds_read_b32 v135, v148 offset:4864
	s_waitcnt vmcnt(4) lgkmcnt(4)
	v_mfma_f32_16x16x4_f32 v[88:91], v132, v136, v[88:91]
	v_mfma_f32_16x16x4_f32 v[92:95], v132, v137, v[92:95]
	v_mfma_f32_16x16x4_f32 v[112:115], v132, v138, v[112:115]
	v_mfma_f32_16x16x4_f32 v[116:119], v132, v139, v[116:119]
	global_load_dwordx4 v[136:139], v149, s[10:11]
	v_add_u32_e32 v149, 0x2000, v149
	ds_read_b32 v132, v148 offset:5120
	s_waitcnt vmcnt(4) lgkmcnt(4)
	v_mfma_f32_16x16x4_f32 v[88:91], v133, v140, v[88:91]
	v_mfma_f32_16x16x4_f32 v[92:95], v133, v141, v[92:95]
	v_mfma_f32_16x16x4_f32 v[112:115], v133, v142, v[112:115]
	v_mfma_f32_16x16x4_f32 v[116:119], v133, v143, v[116:119]
	global_load_dwordx4 v[140:143], v149, s[10:11]
	v_add_u32_e32 v149, 0x2000, v149
	ds_read_b32 v133, v148 offset:5376
	s_waitcnt vmcnt(4) lgkmcnt(4)
	v_mfma_f32_16x16x4_f32 v[88:91], v134, v144, v[88:91]
	v_mfma_f32_16x16x4_f32 v[92:95], v134, v145, v[92:95]
	v_mfma_f32_16x16x4_f32 v[112:115], v134, v146, v[112:115]
	v_mfma_f32_16x16x4_f32 v[116:119], v134, v147, v[116:119]
	global_load_dwordx4 v[144:147], v149, s[10:11]
	v_add_u32_e32 v149, 0x2000, v149
	ds_read_b32 v134, v148 offset:5632
	s_waitcnt vmcnt(4) lgkmcnt(4)
	v_mfma_f32_16x16x4_f32 v[88:91], v155, v156, v[88:91]
	v_mfma_f32_16x16x4_f32 v[92:95], v155, v157, v[92:95]
	v_mfma_f32_16x16x4_f32 v[112:115], v155, v158, v[112:115]
	v_mfma_f32_16x16x4_f32 v[116:119], v155, v159, v[116:119]
	global_load_dwordx4 v[156:159], v149, s[10:11]
	v_add_u32_e32 v149, 0x2000, v149
	ds_read_b32 v155, v148 offset:5888
	s_waitcnt vmcnt(4) lgkmcnt(4)
	v_mfma_f32_16x16x4_f32 v[88:91], v135, v160, v[88:91]
	v_mfma_f32_16x16x4_f32 v[92:95], v135, v161, v[92:95]
	v_mfma_f32_16x16x4_f32 v[112:115], v135, v162, v[112:115]
	v_mfma_f32_16x16x4_f32 v[116:119], v135, v163, v[116:119]
	global_load_dwordx4 v[160:163], v149, s[10:11]
	v_add_u32_e32 v149, 0x2000, v149
	ds_read_b32 v135, v148 offset:6144
	s_waitcnt vmcnt(4) lgkmcnt(4)
	v_mfma_f32_16x16x4_f32 v[88:91], v132, v136, v[88:91]
	v_mfma_f32_16x16x4_f32 v[92:95], v132, v137, v[92:95]
	v_mfma_f32_16x16x4_f32 v[112:115], v132, v138, v[112:115]
	v_mfma_f32_16x16x4_f32 v[116:119], v132, v139, v[116:119]
	global_load_dwordx4 v[136:139], v149, s[10:11]
	v_add_u32_e32 v149, 0x2000, v149
	ds_read_b32 v132, v148 offset:6400
	s_waitcnt vmcnt(4) lgkmcnt(4)
	v_mfma_f32_16x16x4_f32 v[88:91], v133, v140, v[88:91]
	v_mfma_f32_16x16x4_f32 v[92:95], v133, v141, v[92:95]
	v_mfma_f32_16x16x4_f32 v[112:115], v133, v142, v[112:115]
	v_mfma_f32_16x16x4_f32 v[116:119], v133, v143, v[116:119]
	global_load_dwordx4 v[140:143], v149, s[10:11]
	v_add_u32_e32 v149, 0x2000, v149
	ds_read_b32 v133, v148 offset:6656
	s_waitcnt vmcnt(4) lgkmcnt(4)
	v_mfma_f32_16x16x4_f32 v[88:91], v134, v144, v[88:91]
	v_mfma_f32_16x16x4_f32 v[92:95], v134, v145, v[92:95]
	v_mfma_f32_16x16x4_f32 v[112:115], v134, v146, v[112:115]
	v_mfma_f32_16x16x4_f32 v[116:119], v134, v147, v[116:119]
	global_load_dwordx4 v[144:147], v149, s[10:11]
	v_add_u32_e32 v149, 0x2000, v149
	ds_read_b32 v134, v148 offset:6912
	s_waitcnt vmcnt(4) lgkmcnt(4)
	v_mfma_f32_16x16x4_f32 v[88:91], v155, v156, v[88:91]
	v_mfma_f32_16x16x4_f32 v[92:95], v155, v157, v[92:95]
	v_mfma_f32_16x16x4_f32 v[112:115], v155, v158, v[112:115]
	v_mfma_f32_16x16x4_f32 v[116:119], v155, v159, v[116:119]
	global_load_dwordx4 v[156:159], v149, s[10:11]
	v_add_u32_e32 v149, 0x2000, v149
	ds_read_b32 v155, v148 offset:7168
	s_waitcnt vmcnt(4) lgkmcnt(4)
	v_mfma_f32_16x16x4_f32 v[88:91], v135, v160, v[88:91]
	v_mfma_f32_16x16x4_f32 v[92:95], v135, v161, v[92:95]
	v_mfma_f32_16x16x4_f32 v[112:115], v135, v162, v[112:115]
	v_mfma_f32_16x16x4_f32 v[116:119], v135, v163, v[116:119]
	global_load_dwordx4 v[160:163], v149, s[10:11]
	v_add_u32_e32 v149, 0x2000, v149
	ds_read_b32 v135, v148 offset:7424
	s_waitcnt vmcnt(4) lgkmcnt(4)
	v_mfma_f32_16x16x4_f32 v[88:91], v132, v136, v[88:91]
	v_mfma_f32_16x16x4_f32 v[92:95], v132, v137, v[92:95]
	v_mfma_f32_16x16x4_f32 v[112:115], v132, v138, v[112:115]
	v_mfma_f32_16x16x4_f32 v[116:119], v132, v139, v[116:119]
	global_load_dwordx4 v[136:139], v149, s[10:11]
	v_add_u32_e32 v149, 0x2000, v149
	ds_read_b32 v132, v148 offset:7680
	s_waitcnt vmcnt(4) lgkmcnt(4)
	v_mfma_f32_16x16x4_f32 v[88:91], v133, v140, v[88:91]
	v_mfma_f32_16x16x4_f32 v[92:95], v133, v141, v[92:95]
	v_mfma_f32_16x16x4_f32 v[112:115], v133, v142, v[112:115]
	v_mfma_f32_16x16x4_f32 v[116:119], v133, v143, v[116:119]
	global_load_dwordx4 v[140:143], v149, s[10:11]
	v_add_u32_e32 v149, 0x2000, v149
	ds_read_b32 v133, v148 offset:7936
	s_waitcnt vmcnt(4) lgkmcnt(4)
	v_mfma_f32_16x16x4_f32 v[88:91], v134, v144, v[88:91]
	v_mfma_f32_16x16x4_f32 v[92:95], v134, v145, v[92:95]
	v_mfma_f32_16x16x4_f32 v[112:115], v134, v146, v[112:115]
	v_mfma_f32_16x16x4_f32 v[116:119], v134, v147, v[116:119]
	s_waitcnt vmcnt(3) lgkmcnt(3)
	v_mfma_f32_16x16x4_f32 v[88:91], v155, v156, v[88:91]
	v_mfma_f32_16x16x4_f32 v[92:95], v155, v157, v[92:95]
	v_mfma_f32_16x16x4_f32 v[112:115], v155, v158, v[112:115]
	v_mfma_f32_16x16x4_f32 v[116:119], v155, v159, v[116:119]
	s_waitcnt vmcnt(2) lgkmcnt(2)
	v_mfma_f32_16x16x4_f32 v[88:91], v135, v160, v[88:91]
	v_mfma_f32_16x16x4_f32 v[92:95], v135, v161, v[92:95]
	v_mfma_f32_16x16x4_f32 v[112:115], v135, v162, v[112:115]
	v_mfma_f32_16x16x4_f32 v[116:119], v135, v163, v[116:119]
	s_waitcnt vmcnt(1) lgkmcnt(1)
	v_mfma_f32_16x16x4_f32 v[88:91], v132, v136, v[88:91]
	v_mfma_f32_16x16x4_f32 v[92:95], v132, v137, v[92:95]
	v_mfma_f32_16x16x4_f32 v[112:115], v132, v138, v[112:115]
	v_mfma_f32_16x16x4_f32 v[116:119], v132, v139, v[116:119]
	s_waitcnt vmcnt(0) lgkmcnt(0)
	v_mfma_f32_16x16x4_f32 v[88:91], v133, v140, v[88:91]
	v_mfma_f32_16x16x4_f32 v[92:95], v133, v141, v[92:95]
	v_mfma_f32_16x16x4_f32 v[112:115], v133, v142, v[112:115]
	v_mfma_f32_16x16x4_f32 v[116:119], v133, v143, v[116:119]
	s_nop 15
	s_nop 3
	s_mov_b32 s46, 0
	s_mov_b64 s[24:25], -1
	ds_write_b32 v150, v88 offset:0
	ds_write_b32 v150, v89 offset:2048
	ds_write_b32 v150, v90 offset:4096
	ds_write_b32 v150, v91 offset:6144
	ds_write_b32 v150, v92 offset:4
	ds_write_b32 v150, v93 offset:2052
	ds_write_b32 v150, v94 offset:4100
	ds_write_b32 v150, v95 offset:6148
	ds_write_b32 v150, v112 offset:8
	ds_write_b32 v150, v113 offset:2056
	ds_write_b32 v150, v114 offset:4104
	ds_write_b32 v150, v115 offset:6152
	ds_write_b32 v150, v116 offset:12
	ds_write_b32 v150, v117 offset:2060
	ds_write_b32 v150, v118 offset:4108
	ds_write_b32 v150, v119 offset:6156
	s_waitcnt lgkmcnt(0)
	s_barrier
